# adds: static s_setprio 1 for waves 4-7 during MLA; nt (streaming) cache policy on the use-once f32 loads: x rows and the f32 weight tiles read by the bf16 conversion passes in P0, P1 idle half-round a
# speedup vs baseline: 1.0299x; 1.0198x over previous
.LBB0_71:
	s_lshl_b32 s0, s63, 5
	s_add_i32 s6, s0, s54
	s_ashr_i32 s7, s6, 31
	v_ashrrev_i32_e32 v2, 31, v58
	v_lshl_add_u64 v[0:1], s[6:7], 2, v[36:37]
	v_mul_lo_u32 v4, s46, v2
	v_mul_lo_u32 v5, s47, v58
	v_mad_u64_u32 v[2:3], s[6:7], s46, v58, 0
	v_add3_u32 v3, v3, v4, v5
	v_add_u32_e32 v4, 8, v58
	v_ashrrev_i32_e32 v5, 31, v4
	v_mul_lo_u32 v6, s46, v5
	v_mul_lo_u32 v7, s47, v4
	v_mad_u64_u32 v[4:5], s[6:7], s46, v4, 0
	v_lshl_add_u64 v[2:3], v[2:3], 2, v[0:1]
	v_add3_u32 v5, v5, v6, v7
	v_lshl_add_u64 v[4:5], v[4:5], 2, v[0:1]
	global_load_dwordx4 v[28:31], v[2:3], off nt
	global_load_dwordx4 v[20:23], v[4:5], off nt
	v_add_u32_e32 v2, 16, v58
	v_ashrrev_i32_e32 v3, 31, v2
	v_mul_lo_u32 v4, s46, v3
	v_mul_lo_u32 v5, s47, v2
	v_mad_u64_u32 v[2:3], s[6:7], s46, v2, 0
	v_add3_u32 v3, v3, v4, v5
	v_add_u32_e32 v4, 24, v58
	v_ashrrev_i32_e32 v5, 31, v4
	v_mul_lo_u32 v6, s46, v5
	v_mul_lo_u32 v7, s47, v4
	v_mad_u64_u32 v[4:5], s[6:7], s46, v4, 0
	v_lshl_add_u64 v[2:3], v[2:3], 2, v[0:1]
	v_add3_u32 v5, v5, v6, v7
	v_lshl_add_u64 v[4:5], v[4:5], 2, v[0:1]
	global_load_dwordx4 v[24:27], v[2:3], off nt
	global_load_dwordx4 v[12:15], v[4:5], off nt
	v_add_u32_e32 v2, 32, v58
	v_ashrrev_i32_e32 v3, 31, v2
	v_mul_lo_u32 v4, s46, v3
	v_mul_lo_u32 v5, s47, v2
	v_mad_u64_u32 v[2:3], s[6:7], s46, v2, 0
	v_add3_u32 v3, v3, v4, v5
	v_add_u32_e32 v4, 40, v58
	v_ashrrev_i32_e32 v5, 31, v4
	v_mul_lo_u32 v6, s46, v5
	v_mul_lo_u32 v7, s47, v4
	v_mad_u64_u32 v[4:5], s[6:7], s46, v4, 0
	v_add3_u32 v5, v5, v6, v7
	v_lshl_add_u64 v[2:3], v[2:3], 2, v[0:1]
	v_lshl_add_u64 v[4:5], v[4:5], 2, v[0:1]
	global_load_dwordx4 v[16:19], v[2:3], off nt
	s_nop 0
	global_load_dwordx4 v[4:7], v[4:5], off nt
	v_add_u32_e32 v2, 48, v58
	v_ashrrev_i32_e32 v3, 31, v2
	v_mul_lo_u32 v8, s46, v3
	v_mul_lo_u32 v9, s47, v2
	v_mad_u64_u32 v[2:3], s[6:7], s46, v2, 0
	v_add3_u32 v3, v3, v8, v9
	v_add_u32_e32 v8, 56, v58
	v_ashrrev_i32_e32 v9, 31, v8
	v_mul_lo_u32 v10, s46, v9
	v_mul_lo_u32 v11, s47, v8
	v_mad_u64_u32 v[8:9], s[6:7], s46, v8, 0
	v_add3_u32 v9, v9, v10, v11
	v_lshl_add_u64 v[2:3], v[2:3], 2, v[0:1]
	v_lshl_add_u64 v[0:1], v[8:9], 2, v[0:1]
	global_load_dwordx4 v[8:11], v[2:3], off nt
	s_nop 0
	global_load_dwordx4 v[0:3], v[0:1], off nt
	s_and_b64 vcc, exec, s[2:3]
	s_cbranch_vccnz .LBB0_73
	v_add_u32_e32 v60, s50, v40
	v_ashrrev_i32_e32 v61, 31, v60
	v_lshl_add_u64 v[60:61], v[60:61], 2, s[8:9]
	global_load_dword v59, v[60:61], off
	s_branch .LBB0_74

.LBB0_75:
	s_bitcmp0_b32 s63, 2
	s_cselect_b32 s1, s11, s49
	s_cselect_b32 s5, s10, s48
	s_lshl_b32 s0, s63, 4
	s_and_b32 s6, s0, 0xffffff80
	s_lshl_b32 s0, s63, 5
	s_and_b32 s7, s0, 0x60
	s_or_b32 s6, s6, s7
	s_ashr_i32 s7, s6, 31
	s_lshl_b64 s[6:7], s[6:7], 2
	s_add_u32 s6, s5, s6
	s_addc_u32 s7, s1, s7
	v_ashrrev_i32_e32 v2, 31, v58
	v_lshl_add_u64 v[0:1], s[6:7], 0, v[32:33]
	v_mul_lo_u32 v4, s46, v2
	v_mul_lo_u32 v5, s47, v58
	v_mad_u64_u32 v[2:3], s[6:7], s46, v58, 0
	v_add3_u32 v3, v3, v4, v5
	v_add_u32_e32 v4, 8, v58
	v_ashrrev_i32_e32 v5, 31, v4
	v_mul_lo_u32 v6, s46, v5
	v_mul_lo_u32 v7, s47, v4
	v_mad_u64_u32 v[4:5], s[6:7], s46, v4, 0
	v_lshl_add_u64 v[2:3], v[2:3], 2, v[0:1]
	v_add3_u32 v5, v5, v6, v7
	v_lshl_add_u64 v[4:5], v[4:5], 2, v[0:1]
	global_load_dwordx4 v[28:31], v[2:3], off nt
	global_load_dwordx4 v[20:23], v[4:5], off nt
	v_add_u32_e32 v2, 16, v58
	v_ashrrev_i32_e32 v3, 31, v2
	v_mul_lo_u32 v4, s46, v3
	v_mul_lo_u32 v5, s47, v2
	v_mad_u64_u32 v[2:3], s[6:7], s46, v2, 0
	v_add3_u32 v3, v3, v4, v5
	v_add_u32_e32 v4, 24, v58
	v_ashrrev_i32_e32 v5, 31, v4
	v_mul_lo_u32 v6, s46, v5
	v_mul_lo_u32 v7, s47, v4
	v_mad_u64_u32 v[4:5], s[6:7], s46, v4, 0
	v_lshl_add_u64 v[2:3], v[2:3], 2, v[0:1]
	v_add3_u32 v5, v5, v6, v7
	v_lshl_add_u64 v[4:5], v[4:5], 2, v[0:1]
	global_load_dwordx4 v[24:27], v[2:3], off nt
	global_load_dwordx4 v[12:15], v[4:5], off nt
	v_add_u32_e32 v2, 32, v58
	v_ashrrev_i32_e32 v3, 31, v2
	v_mul_lo_u32 v4, s46, v3
	v_mul_lo_u32 v5, s47, v2
	v_mad_u64_u32 v[2:3], s[6:7], s46, v2, 0
	v_add3_u32 v3, v3, v4, v5
	v_add_u32_e32 v4, 40, v58
	v_ashrrev_i32_e32 v5, 31, v4
	v_mul_lo_u32 v6, s46, v5
	v_mul_lo_u32 v7, s47, v4
	v_mad_u64_u32 v[4:5], s[6:7], s46, v4, 0
	v_add3_u32 v5, v5, v6, v7
	v_lshl_add_u64 v[2:3], v[2:3], 2, v[0:1]
	v_lshl_add_u64 v[4:5], v[4:5], 2, v[0:1]
	global_load_dwordx4 v[16:19], v[2:3], off nt
	s_nop 0
	global_load_dwordx4 v[4:7], v[4:5], off nt
	v_add_u32_e32 v2, 48, v58
	v_ashrrev_i32_e32 v3, 31, v2
	v_mul_lo_u32 v8, s46, v3
	v_mul_lo_u32 v9, s47, v2
	v_mad_u64_u32 v[2:3], s[6:7], s46, v2, 0
	v_add3_u32 v3, v3, v8, v9
	v_add_u32_e32 v8, 56, v58
	v_ashrrev_i32_e32 v9, 31, v8
	v_mul_lo_u32 v10, s46, v9
	v_mul_lo_u32 v11, s47, v8
	v_mad_u64_u32 v[8:9], s[6:7], s46, v8, 0
	v_add3_u32 v9, v9, v10, v11
	v_lshl_add_u64 v[2:3], v[2:3], 2, v[0:1]
	v_lshl_add_u64 v[0:1], v[8:9], 2, v[0:1]
	global_load_dwordx4 v[8:11], v[2:3], off nt
	s_nop 0
	global_load_dwordx4 v[0:3], v[0:1], off nt
	s_and_b64 vcc, exec, s[2:3]
	s_cbranch_vccz .LBB0_60
	v_mov_b32_e32 v58, 1.0
	s_branch .LBB0_61

.LBB0_80:
	s_waitcnt lgkmcnt(0)
	global_load_dwordx4 v[12:15], v[2:3], off offset:-2048 nt
	global_load_dwordx4 v[16:19], v[2:3], off offset:-1024 nt
	global_load_dwordx4 v[20:23], v[2:3], off nt
	global_load_dwordx4 v[24:27], v[2:3], off offset:1024 nt
	v_lshl_add_u64 v[28:29], s[20:21], 0, v[0:1]
	v_add_co_u32_e64 v28, s[2:3], s24, v28
	s_waitcnt vmcnt(0)
	v_mul_f32_e32 v11, v13, v13
	v_mul_f32_e32 v30, v15, v15
	s_waitcnt vmcnt(2)
	v_mul_f32_e32 v31, v17, v17
	v_mul_f32_e32 v32, v19, v19
	s_waitcnt vmcnt(1)
	v_mul_f32_e32 v33, v21, v21
	v_mul_f32_e32 v34, v23, v23
	v_fmac_f32_e32 v11, v12, v12
	v_fmac_f32_e32 v30, v14, v14
	v_fmac_f32_e32 v31, v16, v16
	v_fmac_f32_e32 v32, v18, v18
	s_waitcnt vmcnt(0)
	v_mul_f32_e32 v35, v25, v25
	v_mul_f32_e32 v36, v27, v27
	v_fmac_f32_e32 v33, v20, v20
	v_fmac_f32_e32 v34, v22, v22
	v_add_f32_e32 v11, v11, v30
	v_add_f32_e32 v30, v31, v32
	v_fmac_f32_e32 v35, v24, v24
	v_fmac_f32_e32 v36, v26, v26
	v_add_f32_e32 v31, v33, v34
	v_add_f32_e32 v11, v11, v30
	v_add_f32_e32 v32, v35, v36
	v_add_f32_e32 v11, v11, v31
	v_add_f32_e32 v11, v11, v32
	ds_bpermute_b32 v30, v4, v11
	v_bfe_u32 v37, v12, 16, 1
	v_bfe_u32 v39, v14, 16, 1
	v_bfe_u32 v44, v18, 16, 1
	v_bfe_u32 v38, v13, 16, 1
	s_waitcnt lgkmcnt(0)
	v_add_f32_e32 v11, v11, v30
	ds_bpermute_b32 v30, v5, v11
	v_bfe_u32 v41, v15, 16, 1
	v_bfe_u32 v45, v19, 16, 1
	v_add3_u32 v12, v12, v37, s13
	v_add3_u32 v14, v14, v39, s13
	s_waitcnt lgkmcnt(0)
	v_add_f32_e32 v11, v11, v30
	ds_bpermute_b32 v30, v6, v11
	v_add3_u32 v18, v18, v44, s13
	v_add3_u32 v13, v13, v38, s13
	v_add3_u32 v15, v15, v41, s13
	v_add3_u32 v19, v19, v45, s13
	s_waitcnt lgkmcnt(0)
	v_add_f32_e32 v11, v11, v30
	ds_bpermute_b32 v30, v7, v11
	v_lshrrev_b32_e32 v12, 16, v12
	v_lshrrev_b32_e32 v14, 16, v14
	v_lshrrev_b32_e32 v18, 16, v18
	v_and_or_b32 v12, v13, s15, v12
	s_waitcnt lgkmcnt(0)
	v_add_f32_e32 v11, v11, v30
	v_and_or_b32 v13, v15, s15, v14
	v_and_or_b32 v15, v19, s15, v18
	ds_bpermute_b32 v19, v8, v11
	v_bfe_u32 v42, v16, 16, 1
	v_bfe_u32 v46, v20, 16, 1
	v_bfe_u32 v48, v22, 16, 1
	v_bfe_u32 v43, v17, 16, 1
	v_bfe_u32 v47, v21, 16, 1
	v_bfe_u32 v49, v23, 16, 1
	v_add3_u32 v16, v16, v42, s13
	v_add3_u32 v20, v20, v46, s13
	v_add3_u32 v22, v22, v48, s13
	v_addc_co_u32_e64 v29, s[2:3], 0, v29, s[2:3]
	v_add3_u32 v17, v17, v43, s13
	v_add3_u32 v21, v21, v47, s13
	v_add3_u32 v23, v23, v49, s13
	v_lshrrev_b32_e32 v16, 16, v16
	v_lshrrev_b32_e32 v20, 16, v20
	v_lshrrev_b32_e32 v22, 16, v22
	s_waitcnt lgkmcnt(0)
	v_add_f32_e32 v11, v11, v19
	v_and_or_b32 v14, v17, s15, v16
	v_and_or_b32 v16, v21, s15, v20
	v_and_or_b32 v17, v23, s15, v22
	global_store_dwordx2 v[28:29], v[12:13], off
	global_store_dwordx2 v[28:29], v[14:15], off offset:512
	global_store_dwordx2 v[28:29], v[16:17], off offset:1024
	ds_bpermute_b32 v12, v9, v11
	v_bfe_u32 v50, v24, 16, 1
	v_bfe_u32 v52, v26, 16, 1
	v_bfe_u32 v51, v25, 16, 1
	v_add3_u32 v24, v24, v50, s13
	v_add3_u32 v26, v26, v52, s13
	v_bfe_u32 v14, v27, 16, 1
	v_add3_u32 v25, v25, v51, s13
	v_lshrrev_b32_e32 v24, 16, v24
	v_lshrrev_b32_e32 v13, 16, v26
	v_add3_u32 v14, v27, v14, s13
	v_and_or_b32 v18, v25, s15, v24
	v_and_or_b32 v19, v14, s15, v13
	global_store_dwordx2 v[28:29], v[18:19], off offset:1536
	s_and_saveexec_b64 s[10:11], vcc
	s_cbranch_execz .LBB0_79
	s_waitcnt lgkmcnt(0)
	v_add_f32_e32 v11, v11, v12
	v_fmamk_f32 v11, v11, 0x3a800000, v10
	v_mul_f32_e32 v12, 0x4b800000, v11
	v_cmp_gt_f32_e64 s[2:3], s25, v11
	s_add_u32 s28, s20, s22
	s_addc_u32 s29, s21, s23
	v_cndmask_b32_e64 v11, v11, v12, s[2:3]
	v_rsq_f32_e32 v11, v11
	s_nop 0
	v_mul_f32_e32 v12, 0x45800000, v11
	v_cndmask_b32_e64 v11, v11, v12, s[2:3]
	v_mov_b64_e32 v[12:13], s[28:29]
	global_store_dword v[12:13], v11, off
	s_branch .LBB0_79

.LBB0_202:
	v_add_u32_e32 v8, s7, v40
	s_add_i32 s38, s5, s42
	v_add_u32_e32 v2, 0xffff0000, v8
	s_ashr_i32 s39, s38, 31
	v_ashrrev_i32_e32 v3, 31, v2
	v_lshl_add_u64 v[0:1], s[38:39], 2, v[38:39]
	v_mul_lo_u32 v4, s36, v3
	v_mul_lo_u32 v5, s37, v2
	v_mad_u64_u32 v[2:3], s[38:39], s36, v2, 0
	v_add3_u32 v3, v3, v4, v5
	v_add_u32_e32 v4, 0xffff0008, v8
	v_ashrrev_i32_e32 v5, 31, v4
	v_mul_lo_u32 v6, s36, v5
	v_mul_lo_u32 v7, s37, v4
	v_mad_u64_u32 v[4:5], s[38:39], s36, v4, 0
	v_lshl_add_u64 v[2:3], v[2:3], 2, v[0:1]
	v_add3_u32 v5, v5, v6, v7
	v_lshl_add_u64 v[4:5], v[4:5], 2, v[0:1]
	global_load_dwordx4 v[28:31], v[2:3], off nt
	global_load_dwordx4 v[20:23], v[4:5], off nt
	v_add_u32_e32 v2, 0xffff0010, v8
	v_ashrrev_i32_e32 v3, 31, v2
	v_mul_lo_u32 v4, s36, v3
	v_mul_lo_u32 v5, s37, v2
	v_mad_u64_u32 v[2:3], s[38:39], s36, v2, 0
	v_add3_u32 v3, v3, v4, v5
	v_add_u32_e32 v4, 0xffff0018, v8
	v_ashrrev_i32_e32 v5, 31, v4
	v_mul_lo_u32 v6, s36, v5
	v_mul_lo_u32 v7, s37, v4
	v_mad_u64_u32 v[4:5], s[38:39], s36, v4, 0
	v_lshl_add_u64 v[2:3], v[2:3], 2, v[0:1]
	v_add3_u32 v5, v5, v6, v7
	v_lshl_add_u64 v[4:5], v[4:5], 2, v[0:1]
	global_load_dwordx4 v[24:27], v[2:3], off nt
	global_load_dwordx4 v[12:15], v[4:5], off nt
	v_add_u32_e32 v2, 0xffff0020, v8
	v_ashrrev_i32_e32 v3, 31, v2
	v_mul_lo_u32 v4, s36, v3
	v_mul_lo_u32 v5, s37, v2
	v_mad_u64_u32 v[2:3], s[38:39], s36, v2, 0
	v_add3_u32 v3, v3, v4, v5
	v_add_u32_e32 v4, 0xffff0028, v8
	v_ashrrev_i32_e32 v5, 31, v4
	v_mul_lo_u32 v6, s36, v5
	v_mul_lo_u32 v7, s37, v4
	v_mad_u64_u32 v[4:5], s[38:39], s36, v4, 0
	v_add3_u32 v5, v5, v6, v7
	v_lshl_add_u64 v[2:3], v[2:3], 2, v[0:1]
	v_lshl_add_u64 v[4:5], v[4:5], 2, v[0:1]
	global_load_dwordx4 v[16:19], v[2:3], off nt
	s_nop 0
	global_load_dwordx4 v[4:7], v[4:5], off nt
	v_add_u32_e32 v2, 0xffff0030, v8
	v_ashrrev_i32_e32 v3, 31, v2
	v_mul_lo_u32 v9, s36, v3
	v_mul_lo_u32 v10, s37, v2
	v_mad_u64_u32 v[2:3], s[38:39], s36, v2, 0
	v_add_u32_e32 v8, 0xffff0038, v8
	v_add3_u32 v3, v3, v9, v10
	v_ashrrev_i32_e32 v9, 31, v8
	v_mul_lo_u32 v10, s36, v9
	v_mul_lo_u32 v11, s37, v8
	v_mad_u64_u32 v[8:9], s[38:39], s36, v8, 0
	v_add3_u32 v9, v9, v10, v11
	v_lshl_add_u64 v[2:3], v[2:3], 2, v[0:1]
	v_lshl_add_u64 v[0:1], v[8:9], 2, v[0:1]
	global_load_dwordx4 v[8:11], v[2:3], off nt
	s_nop 0
	global_load_dwordx4 v[0:3], v[0:1], off nt
	s_andn2_b64 vcc, exec, s[10:11]
	s_cbranch_vccnz .LBB0_204
	v_add_u32_e32 v56, s7, v53
	v_ashrrev_i32_e32 v57, 31, v56
	v_lshl_add_u64 v[56:57], v[56:57], 2, s[8:9]
	global_load_dword v35, v[56:57], off
	s_branch .LBB0_205

.LBB0_578:
	s_cmpk_eq_i32 s79, 0x100
	s_cselect_b64 s[4:5], -1, 0
	s_and_b64 s[8:9], s[4:5], exec
	s_mov_b64 s[0:1], s[70:71]
	s_cselect_b32 s3, s3, 0
	s_cselect_b32 s34, s2, 0x600
	s_add_i32 s35, s3, s82
	s_load_dwordx2 s[0:1], s[0:1], 0xb8
	s_movk_i32 s27, 0x600
	s_mov_b64 s[2:3], s[70:71]
	s_cmp_ge_i32 s35, s34
	s_waitcnt lgkmcnt(0)
	s_cbranch_scc1 .LBB0_614
	s_bitcmp1_b32 s82, 3
	s_cbranch_scc0 .Lp4_go
	s_sleep 127
	s_sleep 40

.LBB0_672:
	s_lshl_b32 s30, s41, 5
	s_ashr_i32 s31, s30, 31
	v_add_u32_e32 v4, 8, v57
	v_lshl_add_u64 v[0:1], s[30:31], 2, v[40:41]
	v_mad_i64_i32 v[2:3], s[42:43], s26, v57, 0
	v_mad_i64_i32 v[4:5], s[42:43], s26, v4, 0
	v_lshl_add_u64 v[2:3], v[2:3], 2, v[0:1]
	v_lshl_add_u64 v[4:5], v[4:5], 2, v[0:1]
	global_load_dwordx4 v[28:31], v[2:3], off nt
	global_load_dwordx4 v[24:27], v[4:5], off nt
	v_add_u32_e32 v2, 16, v57
	v_add_u32_e32 v4, 24, v57
	v_mad_i64_i32 v[2:3], s[42:43], s26, v2, 0
	v_mad_i64_i32 v[4:5], s[42:43], s26, v4, 0
	v_lshl_add_u64 v[2:3], v[2:3], 2, v[0:1]
	v_lshl_add_u64 v[4:5], v[4:5], 2, v[0:1]
	global_load_dwordx4 v[20:23], v[2:3], off nt
	global_load_dwordx4 v[16:19], v[4:5], off nt
	v_add_u32_e32 v2, 32, v57
	v_add_u32_e32 v4, 40, v57
	v_mad_i64_i32 v[2:3], s[42:43], s26, v2, 0
	v_mad_i64_i32 v[4:5], s[42:43], s26, v4, 0
	v_lshl_add_u64 v[2:3], v[2:3], 2, v[0:1]
	v_lshl_add_u64 v[4:5], v[4:5], 2, v[0:1]
	global_load_dwordx4 v[12:15], v[2:3], off nt
	global_load_dwordx4 v[8:11], v[4:5], off nt
	v_add_u32_e32 v2, 48, v57
	v_add_u32_e32 v4, 56, v57
	v_mad_i64_i32 v[2:3], s[42:43], s26, v2, 0
	v_mad_i64_i32 v[4:5], s[42:43], s26, v4, 0
	v_lshl_add_u64 v[2:3], v[2:3], 2, v[0:1]
	v_lshl_add_u64 v[0:1], v[4:5], 2, v[0:1]
	global_load_dwordx4 v[4:7], v[2:3], off nt
	s_nop 0
	global_load_dwordx4 v[0:3], v[0:1], off nt
	s_and_b64 vcc, exec, s[2:3]
	s_cbranch_vccnz .LBB0_674
	v_add_u32_e32 v58, s28, v168
	v_ashrrev_i32_e32 v59, 31, v58
	v_lshl_add_u64 v[58:59], v[58:59], 2, s[24:25]
	global_load_dword v58, v[58:59], off
	s_branch .LBB0_675

.LBB0_676:
	s_bitcmp0_b32 s41, 2
	s_cselect_b32 s29, s1, s23
	s_cselect_b32 s31, s0, s22
	s_lshl_b32 s30, s41, 4
	s_and_b32 s42, s30, 0xffffff80
	s_lshl_b32 s30, s41, 5
	s_and_b32 s41, s30, 0x60
	s_or_b32 s42, s42, s41
	s_ashr_i32 s43, s42, 31
	s_lshl_b64 s[42:43], s[42:43], 2
	s_add_u32 s42, s31, s42
	s_addc_u32 s43, s29, s43
	v_add_u32_e32 v4, 8, v57
	v_lshl_add_u64 v[0:1], s[42:43], 0, v[34:35]
	v_mad_i64_i32 v[2:3], s[42:43], s26, v57, 0
	v_mad_i64_i32 v[4:5], s[42:43], s26, v4, 0
	v_lshl_add_u64 v[2:3], v[2:3], 2, v[0:1]
	v_lshl_add_u64 v[4:5], v[4:5], 2, v[0:1]
	global_load_dwordx4 v[28:31], v[2:3], off nt
	global_load_dwordx4 v[24:27], v[4:5], off nt
	v_add_u32_e32 v2, 16, v57
	v_add_u32_e32 v4, 24, v57
	v_mad_i64_i32 v[2:3], s[42:43], s26, v2, 0
	v_mad_i64_i32 v[4:5], s[42:43], s26, v4, 0
	v_lshl_add_u64 v[2:3], v[2:3], 2, v[0:1]
	v_lshl_add_u64 v[4:5], v[4:5], 2, v[0:1]
	global_load_dwordx4 v[20:23], v[2:3], off nt
	global_load_dwordx4 v[16:19], v[4:5], off nt
	v_add_u32_e32 v2, 32, v57
	v_add_u32_e32 v4, 40, v57
	v_mad_i64_i32 v[2:3], s[42:43], s26, v2, 0
	v_mad_i64_i32 v[4:5], s[42:43], s26, v4, 0
	v_lshl_add_u64 v[2:3], v[2:3], 2, v[0:1]
	v_lshl_add_u64 v[4:5], v[4:5], 2, v[0:1]
	global_load_dwordx4 v[12:15], v[2:3], off nt
	global_load_dwordx4 v[8:11], v[4:5], off nt
	v_add_u32_e32 v2, 48, v57
	v_add_u32_e32 v4, 56, v57
	v_mad_i64_i32 v[2:3], s[42:43], s26, v2, 0
	v_mad_i64_i32 v[4:5], s[42:43], s26, v4, 0
	v_lshl_add_u64 v[2:3], v[2:3], 2, v[0:1]
	v_lshl_add_u64 v[0:1], v[4:5], 2, v[0:1]
	global_load_dwordx4 v[4:7], v[2:3], off nt
	s_nop 0
	global_load_dwordx4 v[0:3], v[0:1], off nt
	s_and_b64 vcc, exec, s[2:3]
	s_cbranch_vccz .LBB0_667
	v_mov_b32_e32 v57, 1.0
	s_branch .LBB0_668

.LBB0_880:
	s_cmp_lt_u32 s83, 4
	s_cbranch_scc1 .Lmla_noprio
	s_setprio 1

.LBB0_971:
	s_setprio 0
	s_load_dword s79, s[70:71], 0x108
	v_readlane_b32 s84, v248, 10
	v_readlane_b32 s88, v248, 7
	v_readlane_b32 s90, v248, 5
	v_readlane_b32 s62, v248, 2
	v_readlane_b32 s82, v248, 36
	v_readlane_b32 s80, v248, 13
	v_readlane_b32 s81, v248, 12
	v_readlane_b32 s83, v248, 23
	v_readlane_b32 s85, v248, 11
	v_readlane_b32 s86, v248, 9
	v_readlane_b32 s89, v248, 8
	v_readlane_b32 s91, v248, 6
	v_readlane_b32 s87, v248, 4
	v_readlane_b32 s63, v248, 3
	v_readlane_b32 s64, v248, 21
	v_readlane_b32 s7, v248, 22
